# lever 10: retention recurrence moved to the f32 matrix cores (v_mfma_f32_16x16x4_f32, chunk of 16 tokens, 28 MFMA per block per wave) in place of the packed-f32 VALU recurrence; HGRN2 unchanged
# speedup vs baseline: 1.0055x; 1.0036x over previous
.Lgla_ret_setup:
	v_and_b32_e32 v154, 15, v163
	v_bfe_u32 v155, v163, 4, 2
	v_lshrrev_b32_e32 v156, 6, v163
	v_log_f32_e32 v157, v100
	v_lshlrev_b32_e32 v56, 9, v154
	v_lshl_add_u32 v56, v156, 6, v56
	v_lshl_add_u32 v56, v155, 4, v56
	v_lshlrev_b32_e32 v57, 9, v155
	v_lshl_add_u32 v57, v156, 6, v57
	v_lshl_add_u32 v57, v154, 2, v57
	v_lshrrev_b32_e32 v158, 1, v155
	v_and_b32_e32 v159, 1, v155
	v_lshlrev_b32_e32 v58, 8, v158
	v_lshl_add_u32 v58, v154, 4, v58
	v_lshl_add_u32 v58, v159, 3, v58
	v_lshlrev_b32_e32 v158, 10, v154
	v_lshl_add_u32 v158, v156, 7, v158
	v_lshl_add_u32 v158, v155, 4, v158
	v_add_u32_e32 v59, 0x10000, v158
	v_add_u32_e32 v60, 0x14000, v158
	v_add_u32_e32 v160, 1, v154
	v_cvt_f32_i32_e32 v160, v160
	v_mul_f32_e32 v160, v160, v157
	v_exp_f32_e32 v40, v160
	s_nop 0
	v_mov_b32_e32 v41, v40
	v_sub_u32_e32 v160, 15, v155
	v_cvt_f32_i32_e32 v160, v160
	v_mul_f32_e32 v160, v160, v157
	v_exp_f32_e32 v44, v160
	v_sub_u32_e32 v160, 11, v155
	v_cvt_f32_i32_e32 v160, v160
	v_mul_f32_e32 v160, v160, v157
	v_exp_f32_e32 v45, v160
	v_sub_u32_e32 v160, 7, v155
	v_cvt_f32_i32_e32 v160, v160
	v_mul_f32_e32 v160, v160, v157
	v_exp_f32_e32 v46, v160
	v_sub_u32_e32 v160, 3, v155
	v_cvt_f32_i32_e32 v160, v160
	v_mul_f32_e32 v160, v160, v157
	v_exp_f32_e32 v47, v160
	v_lshl_add_u32 v161, v155, 2, 0
	v_add_u32_e32 v160, 1, v161
	v_cvt_f32_i32_e32 v160, v160
	v_mul_f32_e64 v160, -v160, v157
	v_exp_f32_e32 v160, v160
	v_cmp_le_u32_e32 vcc, v161, v154
	s_nop 1
	v_cndmask_b32_e32 v48, 0, v160, vcc
	v_lshl_add_u32 v161, v155, 2, 1
	v_add_u32_e32 v160, 1, v161
	v_cvt_f32_i32_e32 v160, v160
	v_mul_f32_e64 v160, -v160, v157
	v_exp_f32_e32 v160, v160
	v_cmp_le_u32_e32 vcc, v161, v154
	s_nop 1
	v_cndmask_b32_e32 v49, 0, v160, vcc
	v_lshl_add_u32 v161, v155, 2, 2
	v_add_u32_e32 v160, 1, v161
	v_cvt_f32_i32_e32 v160, v160
	v_mul_f32_e64 v160, -v160, v157
	v_exp_f32_e32 v160, v160
	v_cmp_le_u32_e32 vcc, v161, v154
	s_nop 1
	v_cndmask_b32_e32 v50, 0, v160, vcc
	v_lshl_add_u32 v161, v155, 2, 3
	v_add_u32_e32 v160, 1, v161
	v_cvt_f32_i32_e32 v160, v160
	v_mul_f32_e64 v160, -v160, v157
	v_exp_f32_e32 v160, v160
	v_cmp_le_u32_e32 vcc, v161, v154
	s_nop 1
	v_cndmask_b32_e32 v51, 0, v160, vcc
	v_mul_f32_e32 v52, v100, v100
	v_mul_f32_e32 v52, v52, v52
	v_mul_f32_e32 v52, v52, v52
	v_mul_f32_e32 v52, v52, v52
	v_mov_b32_e32 v53, v52
	.p2align 6

.Lgla_st_join_4:
	v_lshlrev_b32_e32 v184, 16, v126
	v_and_b32_e32 v185, s69, v126
	v_lshlrev_b32_e32 v186, 16, v127
	v_and_b32_e32 v187, s69, v127
	v_lshlrev_b32_e32 v188, 16, v119
	v_and_b32_e32 v189, s69, v119
	ds_write_b128 v139, v[180:183] offset:40960
	ds_write_b128 v139, v[184:187] offset:49152
	ds_write2_b32 v153, v188, v189 offset1:4
	global_load_dwordx2 v[126:127], v130, s[8:9]
	global_load_dwordx2 v[190:191], v130, s[8:9] offset:1024
	global_load_dword v119, v131, s[8:9]
	s_add_u32 s8, s8, 0x34000
	s_addc_u32 s9, s9, 0
	s_waitcnt lgkmcnt(3)
	v_add_f32_e32 v112, v104, v105
	v_add_f32_e32 v112, v112, v106
	v_add_f32_e32 v112, v112, v107
	v_add_f32_e32 v112, v112, v108
	v_add_f32_e32 v112, v112, v109
	v_add_f32_e32 v112, v112, v110
	v_add_f32_e32 v112, v112, v111
	v_mul_f32_e32 v113, v112, v112
	v_cvt_pk_bf16_f32 v116, v112, v129
	v_mov_b32_e32 v117, v112
	v_mov_b32_e32 v118, v113
	global_store_short v132, v116, s[10:11]
	s_nop 1
	v_permlane16_swap_b32_e32 v112, v117
	v_permlane16_swap_b32_e32 v113, v118
	v_add_f32_e32 v112, v112, v117
	v_add_f32_e32 v113, v113, v118
	s_nop 1
	v_add_f32_dpp v112, v112, v112 row_ror:8 row_mask:0xf bank_mask:0xf
	v_add_f32_dpp v113, v113, v113 row_ror:8 row_mask:0xf bank_mask:0xf
	s_nop 1
	v_add_f32_dpp v112, v112, v112 row_ror:4 row_mask:0xf bank_mask:0xf
	v_add_f32_dpp v113, v113, v113 row_ror:4 row_mask:0xf bank_mask:0xf
	s_nop 1
	v_add_f32_dpp v112, v112, v112 row_ror:2 row_mask:0xf bank_mask:0xf
	v_add_f32_dpp v113, v113, v113 row_ror:2 row_mask:0xf bank_mask:0xf
	s_nop 1
	v_add_f32_dpp v112, v112, v112 row_ror:1 row_mask:0xf bank_mask:0xf
	v_add_f32_dpp v113, v113, v113 row_ror:1 row_mask:0xf bank_mask:0xf
	v_mov_b32_e32 v114, 0
	v_mov_b32_e32 v115, 0
	s_mov_b64 exec, s[18:19]
	global_store_dwordx4 v133, v[112:115], s[12:13]
	s_mov_b64 exec, -1
	s_cmp_eq_u32 s15, 512
	s_cselect_b32 s20, 0, 0x10000
	s_cselect_b32 s21, 0, 0x1000
	s_add_u32 s10, s10, s20
	s_addc_u32 s11, s11, 0
	s_add_u32 s12, s12, s21
	s_addc_u32 s13, s13, 0
	ds_read_b128 v[20:23], v56 offset:16384
	ds_read_b128 v[24:27], v56 offset:8192
	ds_read_b32 v28, v57 offset:8192
	ds_read_b32 v29, v57 offset:10240
	ds_read_b32 v30, v57 offset:12288
	ds_read_b32 v31, v57 offset:14336
	ds_read_b64 v[32:33], v58 offset:24576
	ds_read_b64 v[34:35], v58 offset:25088
	ds_read_b64 v[36:37], v58 offset:25600
	ds_read_b64 v[38:39], v58 offset:26112
	s_waitcnt lgkmcnt(8)
	v_pk_mul_f32 v[20:21], v[20:21], v[40:41]
	v_pk_mul_f32 v[22:23], v[22:23], v[40:41]
	s_nop 1
	v_mfma_f32_16x16x4_f32 v[16:19], v24, v20, 0
	v_mfma_f32_16x16x4_f32 v[8:11], v0, v20, 0
	v_mfma_f32_16x16x4_f32 v[16:19], v25, v21, v[16:19]
	v_mfma_f32_16x16x4_f32 v[12:15], v4, v20, 0
	v_mfma_f32_16x16x4_f32 v[16:19], v26, v22, v[16:19]
	v_mfma_f32_16x16x4_f32 v[8:11], v1, v21, v[8:11]
	v_mfma_f32_16x16x4_f32 v[16:19], v27, v23, v[16:19]
	v_mfma_f32_16x16x4_f32 v[12:15], v5, v21, v[12:15]
	v_mfma_f32_16x16x4_f32 v[8:11], v2, v22, v[8:11]
	v_mfma_f32_16x16x4_f32 v[12:15], v6, v22, v[12:15]
	v_mfma_f32_16x16x4_f32 v[8:11], v3, v23, v[8:11]
	v_mfma_f32_16x16x4_f32 v[12:15], v7, v23, v[12:15]
	s_waitcnt lgkmcnt(0)
	v_mul_f32_e32 v28, v28, v44
	v_mul_f32_e32 v29, v29, v45
	v_mul_f32_e32 v30, v30, v46
	v_mul_f32_e32 v31, v31, v47
	v_pk_mul_f32 v[0:1], v[0:1], v[52:53]
	v_pk_mul_f32 v[2:3], v[2:3], v[52:53]
	v_pk_mul_f32 v[4:5], v[4:5], v[52:53]
	v_pk_mul_f32 v[6:7], v[6:7], v[52:53]
	v_pk_mul_f32 v[16:17], v[16:17], v[48:49]
	v_pk_mul_f32 v[18:19], v[18:19], v[50:51]
	s_nop 1
	v_permlane16_swap_b32_e32 v16, v17
	v_permlane16_swap_b32_e32 v18, v19
	s_nop 1
	v_permlane32_swap_b32_e32 v16, v18
	v_permlane32_swap_b32_e32 v17, v19
	s_nop 1
	v_mfma_f32_16x16x4_f32 v[8:11], v32, v16, v[8:11]
	v_mfma_f32_16x16x4_f32 v[12:15], v33, v16, v[12:15]
	v_mfma_f32_16x16x4_f32 v[8:11], v34, v17, v[8:11]
	v_mfma_f32_16x16x4_f32 v[12:15], v35, v17, v[12:15]
	v_mfma_f32_16x16x4_f32 v[8:11], v36, v18, v[8:11]
	v_mfma_f32_16x16x4_f32 v[12:15], v37, v18, v[12:15]
	v_mfma_f32_16x16x4_f32 v[8:11], v38, v19, v[8:11]
	v_mfma_f32_16x16x4_f32 v[12:15], v39, v19, v[12:15]
	v_mfma_f32_16x16x4_f32 v[0:3], v28, v32, v[0:3]
	v_mfma_f32_16x16x4_f32 v[4:7], v28, v33, v[4:7]
	v_mfma_f32_16x16x4_f32 v[0:3], v29, v34, v[0:3]
	v_mfma_f32_16x16x4_f32 v[4:7], v29, v35, v[4:7]
	v_mfma_f32_16x16x4_f32 v[0:3], v30, v36, v[0:3]
	v_mfma_f32_16x16x4_f32 v[4:7], v30, v37, v[4:7]
	v_mfma_f32_16x16x4_f32 v[0:3], v31, v38, v[0:3]
	v_mfma_f32_16x16x4_f32 v[4:7], v31, v39, v[4:7]
	s_nop 1
	ds_write_b128 v59, v[8:11]
	ds_write_b128 v59, v[12:15] offset:64
	s_sub_u32 s15, s15, 1
	s_waitcnt lgkmcnt(0)
	s_barrier
	ds_read2_b32 v[104:105], v149 offset0:0 offset1:32
	ds_read2_b32 v[106:107], v149 offset0:64 offset1:96
	ds_read2_b32 v[108:109], v149 offset0:128 offset1:160
	ds_read2_b32 v[110:111], v149 offset0:192 offset1:224
	s_waitcnt vmcnt(7)
	v_lshlrev_b32_e32 v180, 16, v122
	v_and_b32_e32 v181, s69, v122
	v_lshlrev_b32_e32 v182, 16, v123
	v_and_b32_e32 v183, s69, v123
	s_cmp_eq_u32 s14, 0
	s_cbranch_scc1 .Lgla_st_join_5
	v_mul_f32_e32 v180, 0x3fb8aa3b, v180
	v_mul_f32_e32 v181, 0x3fb8aa3b, v181
	v_mul_f32_e32 v182, 0x3fb8aa3b, v182
	v_mul_f32_e32 v183, 0x3fb8aa3b, v183
	v_exp_f32_e32 v180, v180
	v_exp_f32_e32 v181, v181
	v_exp_f32_e32 v182, v182
	v_exp_f32_e32 v183, v183
.Lgla_st_join_5:
	v_lshlrev_b32_e32 v184, 16, v120
	v_and_b32_e32 v185, s69, v120
	v_lshlrev_b32_e32 v186, 16, v121
	v_and_b32_e32 v187, s69, v121
	v_lshlrev_b32_e32 v188, 16, v124
	v_and_b32_e32 v189, s69, v124
	ds_write_b128 v139, v[180:183] offset:8192
	ds_write_b128 v139, v[184:187] offset:16384
	ds_write2_b32 v140, v188, v189 offset1:4
	global_load_dwordx2 v[120:121], v130, s[8:9]
	global_load_dwordx2 v[122:123], v130, s[8:9] offset:1024
	global_load_dword v124, v131, s[8:9]
	s_add_u32 s8, s8, 0x34000
	s_addc_u32 s9, s9, 0
	s_waitcnt lgkmcnt(3)
	v_add_f32_e32 v112, v104, v105
	v_add_f32_e32 v112, v112, v106
	v_add_f32_e32 v112, v112, v107
	v_add_f32_e32 v112, v112, v108
	v_add_f32_e32 v112, v112, v109
	v_add_f32_e32 v112, v112, v110
	v_add_f32_e32 v112, v112, v111
	v_mul_f32_e32 v113, v112, v112
	v_cvt_pk_bf16_f32 v116, v112, v129
	v_mov_b32_e32 v117, v112
	v_mov_b32_e32 v118, v113
	global_store_short v132, v116, s[10:11]
	s_nop 1
	v_permlane16_swap_b32_e32 v112, v117
	v_permlane16_swap_b32_e32 v113, v118
	v_add_f32_e32 v112, v112, v117
	v_add_f32_e32 v113, v113, v118
	s_nop 1
	v_add_f32_dpp v112, v112, v112 row_ror:8 row_mask:0xf bank_mask:0xf
	v_add_f32_dpp v113, v113, v113 row_ror:8 row_mask:0xf bank_mask:0xf
	s_nop 1
	v_add_f32_dpp v112, v112, v112 row_ror:4 row_mask:0xf bank_mask:0xf
	v_add_f32_dpp v113, v113, v113 row_ror:4 row_mask:0xf bank_mask:0xf
	s_nop 1
	v_add_f32_dpp v112, v112, v112 row_ror:2 row_mask:0xf bank_mask:0xf
	v_add_f32_dpp v113, v113, v113 row_ror:2 row_mask:0xf bank_mask:0xf
	s_nop 1
	v_add_f32_dpp v112, v112, v112 row_ror:1 row_mask:0xf bank_mask:0xf
	v_add_f32_dpp v113, v113, v113 row_ror:1 row_mask:0xf bank_mask:0xf
	v_mov_b32_e32 v114, 0
	v_mov_b32_e32 v115, 0
	s_mov_b64 exec, s[18:19]
	global_store_dwordx4 v133, v[112:115], s[12:13]
	s_mov_b64 exec, -1
	s_cmp_eq_u32 s15, 512
	s_cselect_b32 s20, 0, 0x10000
	s_cselect_b32 s21, 0, 0x1000
	s_add_u32 s10, s10, s20
	s_addc_u32 s11, s11, 0
	s_add_u32 s12, s12, s21
	s_addc_u32 s13, s13, 0
	ds_read_b128 v[20:23], v56 offset:49152
	ds_read_b128 v[24:27], v56 offset:40960
	ds_read_b32 v28, v57 offset:40960
	ds_read_b32 v29, v57 offset:43008
	ds_read_b32 v30, v57 offset:45056
	ds_read_b32 v31, v57 offset:47104
	ds_read_b64 v[32:33], v58 offset:57344
	ds_read_b64 v[34:35], v58 offset:57856
	ds_read_b64 v[36:37], v58 offset:58368
	ds_read_b64 v[38:39], v58 offset:58880
	s_waitcnt lgkmcnt(8)
	v_pk_mul_f32 v[20:21], v[20:21], v[40:41]
	v_pk_mul_f32 v[22:23], v[22:23], v[40:41]
	s_nop 1
	v_mfma_f32_16x16x4_f32 v[16:19], v24, v20, 0
	v_mfma_f32_16x16x4_f32 v[8:11], v0, v20, 0
	v_mfma_f32_16x16x4_f32 v[16:19], v25, v21, v[16:19]
	v_mfma_f32_16x16x4_f32 v[12:15], v4, v20, 0
	v_mfma_f32_16x16x4_f32 v[16:19], v26, v22, v[16:19]
	v_mfma_f32_16x16x4_f32 v[8:11], v1, v21, v[8:11]
	v_mfma_f32_16x16x4_f32 v[16:19], v27, v23, v[16:19]
	v_mfma_f32_16x16x4_f32 v[12:15], v5, v21, v[12:15]
	v_mfma_f32_16x16x4_f32 v[8:11], v2, v22, v[8:11]
	v_mfma_f32_16x16x4_f32 v[12:15], v6, v22, v[12:15]
	v_mfma_f32_16x16x4_f32 v[8:11], v3, v23, v[8:11]
	v_mfma_f32_16x16x4_f32 v[12:15], v7, v23, v[12:15]
	s_waitcnt lgkmcnt(0)
	v_mul_f32_e32 v28, v28, v44
	v_mul_f32_e32 v29, v29, v45
	v_mul_f32_e32 v30, v30, v46
	v_mul_f32_e32 v31, v31, v47
	v_pk_mul_f32 v[0:1], v[0:1], v[52:53]
	v_pk_mul_f32 v[2:3], v[2:3], v[52:53]
	v_pk_mul_f32 v[4:5], v[4:5], v[52:53]
	v_pk_mul_f32 v[6:7], v[6:7], v[52:53]
	v_pk_mul_f32 v[16:17], v[16:17], v[48:49]
	v_pk_mul_f32 v[18:19], v[18:19], v[50:51]
	s_nop 1
	v_permlane16_swap_b32_e32 v16, v17
	v_permlane16_swap_b32_e32 v18, v19
	s_nop 1
	v_permlane32_swap_b32_e32 v16, v18
	v_permlane32_swap_b32_e32 v17, v19
	s_nop 1
	v_mfma_f32_16x16x4_f32 v[8:11], v32, v16, v[8:11]
	v_mfma_f32_16x16x4_f32 v[12:15], v33, v16, v[12:15]
	v_mfma_f32_16x16x4_f32 v[8:11], v34, v17, v[8:11]
	v_mfma_f32_16x16x4_f32 v[12:15], v35, v17, v[12:15]
	v_mfma_f32_16x16x4_f32 v[8:11], v36, v18, v[8:11]
	v_mfma_f32_16x16x4_f32 v[12:15], v37, v18, v[12:15]
	v_mfma_f32_16x16x4_f32 v[8:11], v38, v19, v[8:11]
	v_mfma_f32_16x16x4_f32 v[12:15], v39, v19, v[12:15]
	v_mfma_f32_16x16x4_f32 v[0:3], v28, v32, v[0:3]
	v_mfma_f32_16x16x4_f32 v[4:7], v28, v33, v[4:7]
	v_mfma_f32_16x16x4_f32 v[0:3], v29, v34, v[0:3]
	v_mfma_f32_16x16x4_f32 v[4:7], v29, v35, v[4:7]
	v_mfma_f32_16x16x4_f32 v[0:3], v30, v36, v[0:3]
	v_mfma_f32_16x16x4_f32 v[4:7], v30, v37, v[4:7]
	v_mfma_f32_16x16x4_f32 v[0:3], v31, v38, v[0:3]
	v_mfma_f32_16x16x4_f32 v[4:7], v31, v39, v[4:7]
	s_nop 1
	ds_write_b128 v60, v[8:11]
	ds_write_b128 v60, v[12:15] offset:64
	s_sub_u32 s15, s15, 1
	s_waitcnt lgkmcnt(0)
	s_barrier
	s_cmp_lg_u32 s15, 0
	s_cbranch_scc1 .Lgla_loop_ret
